# out-proj epilogue rewritten: residual loads issued 5 steps ahead with counted vmcnt instead of a vmcnt(0) round trip per step (on top of attention stagger + pipelined loop body)
# speedup vs baseline: 1.0100x; 1.0022x over previous
; DI unsigned cvtpk(float lo, float hi) { f32x2 v = {lo, hi}; bf16x2_t b = __builtin_convertvector(v, bf16x2_t); return __builtin_bit_cast(unsigned, b); }
;     DI void operator()(const f32x4 (&acc)[2][2][4][2], const pg8::Unit& u, int wr, int wc, int fr, int fq) const {
;         const bool is_ctx = u.pm >= 128; const int b = is_ctx ? 8 : (u.pm >> 4);
;         const int mode = is_ctx ? 0 : (layer == 0 ? 1 : 2);
;         const float* gate = modl + b * DIN + 2 * DM;
;         const int row0 = (is_ctx ? (u.pm - 128) : u.pm) * 256 + wr * 64 + fr; const int col0 = u.pn * 256 + wc * 32 + 8 * fq;
;         f32x4 gv[2][2];
; #pragma unroll
;         for (int bj = 0; bj < 2; ++bj)
; #pragma unroll
;             for (int n = 0; n < 2; ++n) gv[bj][n] = *(const f32x4*)(gate + col0 + bj * 128 + 4 * n);
; #pragma unroll
;         for (int ai = 0; ai < 2; ++ai)
; #pragma unroll
;             for (int m = 0; m < 4; ++m) { const size_t off = (size_t)(row0 + ai * 128 + m * 16) * DM + col0;
; #pragma unroll
;                 for (int bj = 0; bj < 2; ++bj) {
;                     f32x4 x0, x1;
;                     if (mode == 2) { const u32x4 w = *(const u32x4*)(xin_b + off + bj * 128);
;                         x0 = (f32x4){bf_lo(w.x), bf_hi(w.x), bf_lo(w.y), bf_hi(w.y)}; x1 = (f32x4){bf_lo(w.z), bf_hi(w.z), bf_lo(w.w), bf_hi(w.w)}; }
;                     else { const float* src = is_ctx ? cin : xin; x0 = *(const f32x4*)(src + off + bj * 128); x1 = *(const f32x4*)(src + off + bj * 128 + 4); }
;                     const f32x4 y0 = x0 + gv[bj][0] * acc[ai][bj][m][0], y1 = x1 + gv[bj][1] * acc[ai][bj][m][1];
;                     if (mode == 1) { u32x4 o; o.x = cvtpk(y0[0], y0[1]); o.y = cvtpk(y0[2], y0[3]); o.z = cvtpk(y1[0], y1[1]); o.w = cvtpk(y1[2], y1[3]); *(u32x4*)(xout_b + off + bj * 128) = o; }
;                     else { float* dst = is_ctx ? cout : xout; *(f32x4*)(dst + off + bj * 128) = y0; *(f32x4*)(dst + off + bj * 128 + 4) = y1; }
;                 }
;             }
;     }
.LBB0_420:
	v_readlane_b32 s70, v255, 51
	v_readlane_b32 s71, v255, 52
	s_lshl_b32 s11, s38, 8
	s_lshr_b32 s12, s38, 4
	s_mul_i32 s12, s12, 0x1800
	s_cmpk_gt_i32 s38, 0x7f
	s_cselect_b32 s12, 0xc000, s12
	s_cselect_b32 s10, 0xffff8000, 0
	s_cselect_b32 s37, 1, 0
	s_add_i32 s11, s11, s10
	v_lshl_or_b32 v158, s36, 8, v168
	v_add_u32_e32 v160, s11, v166
	s_lshl_b32 s12, s12, 2
	s_add_u32 s10, s14, s12
	s_addc_u32 s11, s15, 0
	s_add_u32 s10, s10, 0x4000
	s_addc_u32 s11, s11, 0
	v_lshlrev_b32_e32 v164, 2, v158
	v_lshl_add_u32 v161, v160, 11, v158
	global_load_dwordx4 v[72:75], v164, s[10:11]
	global_load_dwordx4 v[68:71], v164, s[10:11] offset:16
	global_load_dwordx4 v[60:63], v164, s[10:11] offset:512
	global_load_dwordx4 v[56:59], v164, s[10:11] offset:528
	s_cmp_lg_u32 s37, 0
	s_cbranch_scc1 .Lepi4_ctx
	s_cmp_lg_u64 s[20:21], 0
	s_cbranch_scc1 .Lepi4_l0
	v_lshlrev_b32_e32 v162, 1, v161
	v_lshlrev_b32_e32 v163, 2, v161
	s_add_u32 s6, s54, 0x0
	s_addc_u32 s7, s55, 0
	global_load_dwordx4 v[172:175], v162, s[6:7]
	global_load_dwordx4 v[180:183], v162, s[6:7] offset:256
	s_add_u32 s6, s54, 0x10000
	s_addc_u32 s7, s55, 0
	global_load_dwordx4 v[188:191], v162, s[6:7]
	global_load_dwordx4 v[196:199], v162, s[6:7] offset:256
	s_add_u32 s6, s54, 0x20000
	s_addc_u32 s7, s55, 0
	global_load_dwordx4 v[204:207], v162, s[6:7]
	s_waitcnt vmcnt(4)
	v_lshlrev_b32_e32 v176, 16, v174
	v_and_b32_e32 v177, 0xffff0000, v174
	v_lshlrev_b32_e32 v178, 16, v175
	v_and_b32_e32 v179, 0xffff0000, v175
	v_lshlrev_b32_e32 v174, 16, v173
	v_and_b32_e32 v175, 0xffff0000, v173
	v_and_b32_e32 v173, 0xffff0000, v172
	v_lshlrev_b32_e32 v172, 16, v172
	v_pk_fma_f32 v[142:143], v[142:143], v[74:75], v[174:175]
	v_pk_fma_f32 v[140:141], v[140:141], v[72:73], v[172:173]
	v_pk_fma_f32 v[138:139], v[138:139], v[70:71], v[178:179]
	v_pk_fma_f32 v[136:137], v[136:137], v[68:69], v[176:177]
	global_load_dwordx4 v[172:175], v162, s[6:7] offset:256
	s_add_u32 s8, s80, 0x0
	s_addc_u32 s9, s81, 0
	global_store_dwordx4 v163, v[140:143], s[8:9]
	global_store_dwordx4 v163, v[136:139], s[8:9] offset:16
	s_waitcnt vmcnt(6)
	v_lshlrev_b32_e32 v184, 16, v182
	v_and_b32_e32 v185, 0xffff0000, v182
	v_lshlrev_b32_e32 v186, 16, v183
	v_and_b32_e32 v187, 0xffff0000, v183
	v_lshlrev_b32_e32 v182, 16, v181
	v_and_b32_e32 v183, 0xffff0000, v181
	v_and_b32_e32 v181, 0xffff0000, v180
	v_lshlrev_b32_e32 v180, 16, v180
	v_pk_fma_f32 v[134:135], v[134:135], v[62:63], v[182:183]
	v_pk_fma_f32 v[132:133], v[132:133], v[60:61], v[180:181]
	v_pk_fma_f32 v[130:131], v[130:131], v[58:59], v[186:187]
	v_pk_fma_f32 v[128:129], v[128:129], v[56:57], v[184:185]
	s_add_u32 s6, s54, 0x30000
	s_addc_u32 s7, s55, 0
	global_load_dwordx4 v[180:183], v162, s[6:7]
	global_store_dwordx4 v163, v[132:135], s[8:9] offset:512
	global_store_dwordx4 v163, v[128:131], s[8:9] offset:528
	s_waitcnt vmcnt(8)
	v_lshlrev_b32_e32 v192, 16, v190
	v_and_b32_e32 v193, 0xffff0000, v190
	v_lshlrev_b32_e32 v194, 16, v191
	v_and_b32_e32 v195, 0xffff0000, v191
	v_lshlrev_b32_e32 v190, 16, v189
	v_and_b32_e32 v191, 0xffff0000, v189
	v_and_b32_e32 v189, 0xffff0000, v188
	v_lshlrev_b32_e32 v188, 16, v188
	v_pk_fma_f32 v[126:127], v[126:127], v[74:75], v[190:191]
	v_pk_fma_f32 v[124:125], v[124:125], v[72:73], v[188:189]
	v_pk_fma_f32 v[122:123], v[122:123], v[70:71], v[194:195]
	v_pk_fma_f32 v[120:121], v[120:121], v[68:69], v[192:193]
	global_load_dwordx4 v[188:191], v162, s[6:7] offset:256
	s_add_u32 s8, s80, 0x20000
	s_addc_u32 s9, s81, 0
	global_store_dwordx4 v163, v[124:127], s[8:9]
	global_store_dwordx4 v163, v[120:123], s[8:9] offset:16
	s_waitcnt vmcnt(10)
	v_lshlrev_b32_e32 v200, 16, v198
	v_and_b32_e32 v201, 0xffff0000, v198
	v_lshlrev_b32_e32 v202, 16, v199
	v_and_b32_e32 v203, 0xffff0000, v199
	v_lshlrev_b32_e32 v198, 16, v197
	v_and_b32_e32 v199, 0xffff0000, v197
	v_and_b32_e32 v197, 0xffff0000, v196
	v_lshlrev_b32_e32 v196, 16, v196
	v_pk_fma_f32 v[118:119], v[118:119], v[62:63], v[198:199]
	v_pk_fma_f32 v[116:117], v[116:117], v[60:61], v[196:197]
	v_pk_fma_f32 v[114:115], v[114:115], v[58:59], v[202:203]
	v_pk_fma_f32 v[112:113], v[112:113], v[56:57], v[200:201]
	s_add_u32 s6, s54, 0x80000
	s_addc_u32 s7, s55, 0
	global_load_dwordx4 v[196:199], v162, s[6:7]
	global_store_dwordx4 v163, v[116:119], s[8:9] offset:512
	global_store_dwordx4 v163, v[112:115], s[8:9] offset:528
	s_waitcnt vmcnt(12)
	v_lshlrev_b32_e32 v208, 16, v206
	v_and_b32_e32 v209, 0xffff0000, v206
	v_lshlrev_b32_e32 v210, 16, v207
	v_and_b32_e32 v211, 0xffff0000, v207
	v_lshlrev_b32_e32 v206, 16, v205
	v_and_b32_e32 v207, 0xffff0000, v205
	v_and_b32_e32 v205, 0xffff0000, v204
	v_lshlrev_b32_e32 v204, 16, v204
	v_pk_fma_f32 v[110:111], v[110:111], v[74:75], v[206:207]
	v_pk_fma_f32 v[108:109], v[108:109], v[72:73], v[204:205]
	v_pk_fma_f32 v[106:107], v[106:107], v[70:71], v[210:211]
	v_pk_fma_f32 v[104:105], v[104:105], v[68:69], v[208:209]
	global_load_dwordx4 v[204:207], v162, s[6:7] offset:256
	s_add_u32 s8, s80, 0x40000
	s_addc_u32 s9, s81, 0
	global_store_dwordx4 v163, v[108:111], s[8:9]
	global_store_dwordx4 v163, v[104:107], s[8:9] offset:16
	s_waitcnt vmcnt(14)
	v_lshlrev_b32_e32 v176, 16, v174
	v_and_b32_e32 v177, 0xffff0000, v174
	v_lshlrev_b32_e32 v178, 16, v175
	v_and_b32_e32 v179, 0xffff0000, v175
	v_lshlrev_b32_e32 v174, 16, v173
	v_and_b32_e32 v175, 0xffff0000, v173
	v_and_b32_e32 v173, 0xffff0000, v172
	v_lshlrev_b32_e32 v172, 16, v172
	v_pk_fma_f32 v[102:103], v[102:103], v[62:63], v[174:175]
	v_pk_fma_f32 v[100:101], v[100:101], v[60:61], v[172:173]
	v_pk_fma_f32 v[98:99], v[98:99], v[58:59], v[178:179]
	v_pk_fma_f32 v[96:97], v[96:97], v[56:57], v[176:177]
	s_add_u32 s6, s54, 0x90000
	s_addc_u32 s7, s55, 0
	global_load_dwordx4 v[172:175], v162, s[6:7]
	global_store_dwordx4 v163, v[100:103], s[8:9] offset:512
	global_store_dwordx4 v163, v[96:99], s[8:9] offset:528
	s_waitcnt vmcnt(14)
; DI unsigned cvtpk(float lo, float hi) { f32x2 v = {lo, hi}; bf16x2_t b = __builtin_convertvector(v, bf16x2_t); return __builtin_bit_cast(unsigned, b); }
;     DI void operator()(const f32x4 (&acc)[2][2][4][2], const pg8::Unit& u, int wr, int wc, int fr, int fq) const {
;     ...
;                 for (int bj = 0; bj < 2; ++bj) {
;                     f32x4 x0, x1;
;                     if (mode == 2) { const u32x4 w = *(const u32x4*)(xin_b + off + bj * 128);
;                         x0 = (f32x4){bf_lo(w.x), bf_hi(w.x), bf_lo(w.y), bf_hi(w.y)}; x1 = (f32x4){bf_lo(w.z), bf_hi(w.z), bf_lo(w.w), bf_hi(w.w)}; }
;                     else { const float* src = is_ctx ? cin : xin; x0 = *(const f32x4*)(src + off + bj * 128); x1 = *(const f32x4*)(src + off + bj * 128 + 4); }
;                     const f32x4 y0 = x0 + gv[bj][0] * acc[ai][bj][m][0], y1 = x1 + gv[bj][1] * acc[ai][bj][m][1];
;                     if (mode == 1) { u32x4 o; o.x = cvtpk(y0[0], y0[1]); o.y = cvtpk(y0[2], y0[3]); o.z = cvtpk(y1[0], y1[1]); o.w = cvtpk(y1[2], y1[3]); *(u32x4*)(xout_b + off + bj * 128) = o; }
;                     else { float* dst = is_ctx ? cout : xout; *(f32x4*)(dst + off + bj * 128) = y0; *(f32x4*)(dst + off + bj * 128 + 4) = y1; }
;                 }
	v_lshlrev_b32_e32 v184, 16, v182
	v_and_b32_e32 v185, 0xffff0000, v182
	v_lshlrev_b32_e32 v186, 16, v183
	v_and_b32_e32 v187, 0xffff0000, v183
	v_lshlrev_b32_e32 v182, 16, v181
	v_and_b32_e32 v183, 0xffff0000, v181
	v_and_b32_e32 v181, 0xffff0000, v180
	v_lshlrev_b32_e32 v180, 16, v180
	v_pk_fma_f32 v[94:95], v[94:95], v[74:75], v[182:183]
	v_pk_fma_f32 v[92:93], v[92:93], v[72:73], v[180:181]
	v_pk_fma_f32 v[90:91], v[90:91], v[70:71], v[186:187]
	v_pk_fma_f32 v[88:89], v[88:89], v[68:69], v[184:185]
	global_load_dwordx4 v[180:183], v162, s[6:7] offset:256
	s_add_u32 s8, s80, 0x60000
	s_addc_u32 s9, s81, 0
	global_store_dwordx4 v163, v[92:95], s[8:9]
	global_store_dwordx4 v163, v[88:91], s[8:9] offset:16
	s_waitcnt vmcnt(14)
	v_lshlrev_b32_e32 v192, 16, v190
	v_and_b32_e32 v193, 0xffff0000, v190
	v_lshlrev_b32_e32 v194, 16, v191
	v_and_b32_e32 v195, 0xffff0000, v191
	v_lshlrev_b32_e32 v190, 16, v189
	v_and_b32_e32 v191, 0xffff0000, v189
	v_and_b32_e32 v189, 0xffff0000, v188
	v_lshlrev_b32_e32 v188, 16, v188
	v_pk_fma_f32 v[86:87], v[86:87], v[62:63], v[190:191]
	v_pk_fma_f32 v[84:85], v[84:85], v[60:61], v[188:189]
	v_pk_fma_f32 v[82:83], v[82:83], v[58:59], v[194:195]
	v_pk_fma_f32 v[80:81], v[80:81], v[56:57], v[192:193]
	s_add_u32 s6, s54, 0xa0000
	s_addc_u32 s7, s55, 0
	global_load_dwordx4 v[188:191], v162, s[6:7]
	global_store_dwordx4 v163, v[84:87], s[8:9] offset:512
	global_store_dwordx4 v163, v[80:83], s[8:9] offset:528
	s_waitcnt vmcnt(14)
	v_lshlrev_b32_e32 v200, 16, v198
	v_and_b32_e32 v201, 0xffff0000, v198
	v_lshlrev_b32_e32 v202, 16, v199
	v_and_b32_e32 v203, 0xffff0000, v199
	v_lshlrev_b32_e32 v198, 16, v197
	v_and_b32_e32 v199, 0xffff0000, v197
	v_and_b32_e32 v197, 0xffff0000, v196
	v_lshlrev_b32_e32 v196, 16, v196
	v_pk_fma_f32 v[78:79], v[78:79], v[74:75], v[198:199]
	v_pk_fma_f32 v[76:77], v[76:77], v[72:73], v[196:197]
	v_pk_fma_f32 v[66:67], v[66:67], v[70:71], v[202:203]
	v_pk_fma_f32 v[64:65], v[64:65], v[68:69], v[200:201]
	global_load_dwordx4 v[196:199], v162, s[6:7] offset:256
	s_add_u32 s8, s80, 0x100000
	s_addc_u32 s9, s81, 0
	global_store_dwordx4 v163, v[76:79], s[8:9]
	global_store_dwordx4 v163, v[64:67], s[8:9] offset:16
	s_waitcnt vmcnt(14)
	v_lshlrev_b32_e32 v208, 16, v206
	v_and_b32_e32 v209, 0xffff0000, v206
	v_lshlrev_b32_e32 v210, 16, v207
	v_and_b32_e32 v211, 0xffff0000, v207
	v_lshlrev_b32_e32 v206, 16, v205
	v_and_b32_e32 v207, 0xffff0000, v205
	v_and_b32_e32 v205, 0xffff0000, v204
	v_lshlrev_b32_e32 v204, 16, v204
	v_pk_fma_f32 v[54:55], v[54:55], v[62:63], v[206:207]
	v_pk_fma_f32 v[52:53], v[52:53], v[60:61], v[204:205]
	v_pk_fma_f32 v[50:51], v[50:51], v[58:59], v[210:211]
	v_pk_fma_f32 v[48:49], v[48:49], v[56:57], v[208:209]
	s_add_u32 s6, s54, 0xb0000
	s_addc_u32 s7, s55, 0
	global_load_dwordx4 v[204:207], v162, s[6:7]
	global_store_dwordx4 v163, v[52:55], s[8:9] offset:512
	global_store_dwordx4 v163, v[48:51], s[8:9] offset:528
	s_waitcnt vmcnt(14)
	v_lshlrev_b32_e32 v176, 16, v174
	v_and_b32_e32 v177, 0xffff0000, v174
	v_lshlrev_b32_e32 v178, 16, v175
	v_and_b32_e32 v179, 0xffff0000, v175
	v_lshlrev_b32_e32 v174, 16, v173
	v_and_b32_e32 v175, 0xffff0000, v173
	v_and_b32_e32 v173, 0xffff0000, v172
	v_lshlrev_b32_e32 v172, 16, v172
	v_pk_fma_f32 v[46:47], v[46:47], v[74:75], v[174:175]
	v_pk_fma_f32 v[44:45], v[44:45], v[72:73], v[172:173]
	v_pk_fma_f32 v[42:43], v[42:43], v[70:71], v[178:179]
	v_pk_fma_f32 v[40:41], v[40:41], v[68:69], v[176:177]
	global_load_dwordx4 v[172:175], v162, s[6:7] offset:256
	s_add_u32 s8, s80, 0x120000
	s_addc_u32 s9, s81, 0
	global_store_dwordx4 v163, v[44:47], s[8:9]
	global_store_dwordx4 v163, v[40:43], s[8:9] offset:16
	s_waitcnt vmcnt(14)
	v_lshlrev_b32_e32 v184, 16, v182
	v_and_b32_e32 v185, 0xffff0000, v182
	v_lshlrev_b32_e32 v186, 16, v183
	v_and_b32_e32 v187, 0xffff0000, v183
	v_lshlrev_b32_e32 v182, 16, v181
	v_and_b32_e32 v183, 0xffff0000, v181
	v_and_b32_e32 v181, 0xffff0000, v180
	v_lshlrev_b32_e32 v180, 16, v180
	v_pk_fma_f32 v[38:39], v[38:39], v[62:63], v[182:183]
	v_pk_fma_f32 v[36:37], v[36:37], v[60:61], v[180:181]
	v_pk_fma_f32 v[34:35], v[34:35], v[58:59], v[186:187]
	v_pk_fma_f32 v[32:33], v[32:33], v[56:57], v[184:185]
	global_store_dwordx4 v163, v[36:39], s[8:9] offset:512
	global_store_dwordx4 v163, v[32:35], s[8:9] offset:528
	s_waitcnt vmcnt(13)
	v_lshlrev_b32_e32 v192, 16, v190
	v_and_b32_e32 v193, 0xffff0000, v190
	v_lshlrev_b32_e32 v194, 16, v191
	v_and_b32_e32 v195, 0xffff0000, v191
	v_lshlrev_b32_e32 v190, 16, v189
	v_and_b32_e32 v191, 0xffff0000, v189
	v_and_b32_e32 v189, 0xffff0000, v188
	v_lshlrev_b32_e32 v188, 16, v188
	v_pk_fma_f32 v[30:31], v[30:31], v[74:75], v[190:191]
	v_pk_fma_f32 v[28:29], v[28:29], v[72:73], v[188:189]
	v_pk_fma_f32 v[26:27], v[26:27], v[70:71], v[194:195]
	v_pk_fma_f32 v[24:25], v[24:25], v[68:69], v[192:193]
	s_add_u32 s8, s80, 0x140000
	s_addc_u32 s9, s81, 0
	global_store_dwordx4 v163, v[28:31], s[8:9]
	global_store_dwordx4 v163, v[24:27], s[8:9] offset:16
	s_waitcnt vmcnt(12)
	v_lshlrev_b32_e32 v200, 16, v198
	v_and_b32_e32 v201, 0xffff0000, v198
	v_lshlrev_b32_e32 v202, 16, v199
	v_and_b32_e32 v203, 0xffff0000, v199
	v_lshlrev_b32_e32 v198, 16, v197
	v_and_b32_e32 v199, 0xffff0000, v197
	v_and_b32_e32 v197, 0xffff0000, v196
	v_lshlrev_b32_e32 v196, 16, v196
	v_pk_fma_f32 v[22:23], v[22:23], v[62:63], v[198:199]
	v_pk_fma_f32 v[20:21], v[20:21], v[60:61], v[196:197]
	v_pk_fma_f32 v[18:19], v[18:19], v[58:59], v[202:203]
	v_pk_fma_f32 v[16:17], v[16:17], v[56:57], v[200:201]
	global_store_dwordx4 v163, v[20:23], s[8:9] offset:512
	global_store_dwordx4 v163, v[16:19], s[8:9] offset:528
	s_waitcnt vmcnt(11)
	v_lshlrev_b32_e32 v208, 16, v206
	v_and_b32_e32 v209, 0xffff0000, v206
	v_lshlrev_b32_e32 v210, 16, v207
	v_and_b32_e32 v211, 0xffff0000, v207
	v_lshlrev_b32_e32 v206, 16, v205
	v_and_b32_e32 v207, 0xffff0000, v205
	v_and_b32_e32 v205, 0xffff0000, v204
	v_lshlrev_b32_e32 v204, 16, v204
	v_pk_fma_f32 v[14:15], v[14:15], v[74:75], v[206:207]
	v_pk_fma_f32 v[12:13], v[12:13], v[72:73], v[204:205]
	v_pk_fma_f32 v[10:11], v[10:11], v[70:71], v[210:211]
	v_pk_fma_f32 v[8:9], v[8:9], v[68:69], v[208:209]
	s_add_u32 s8, s80, 0x160000
	s_addc_u32 s9, s81, 0
	global_store_dwordx4 v163, v[12:15], s[8:9]
	global_store_dwordx4 v163, v[8:11], s[8:9] offset:16
	s_waitcnt vmcnt(10)
	v_lshlrev_b32_e32 v176, 16, v174
	v_and_b32_e32 v177, 0xffff0000, v174
	v_lshlrev_b32_e32 v178, 16, v175
	v_and_b32_e32 v179, 0xffff0000, v175
	v_lshlrev_b32_e32 v174, 16, v173
	v_and_b32_e32 v175, 0xffff0000, v173
	v_and_b32_e32 v173, 0xffff0000, v172
	v_lshlrev_b32_e32 v172, 16, v172
	v_pk_fma_f32 v[6:7], v[6:7], v[62:63], v[174:175]
	v_pk_fma_f32 v[4:5], v[4:5], v[60:61], v[172:173]
	v_pk_fma_f32 v[2:3], v[2:3], v[58:59], v[178:179]
	v_pk_fma_f32 v[0:1], v[0:1], v[56:57], v[176:177]
	global_store_dwordx4 v163, v[4:7], s[8:9] offset:512
	global_store_dwordx4 v163, v[0:3], s[8:9] offset:528
	s_branch .LBB0_546
; DI unsigned cvtpk(float lo, float hi) { f32x2 v = {lo, hi}; bf16x2_t b = __builtin_convertvector(v, bf16x2_t); return __builtin_bit_cast(unsigned, b); }
;     DI void operator()(const f32x4 (&acc)[2][2][4][2], const pg8::Unit& u, int wr, int wc, int fr, int fq) const {
;     ...
;                 for (int bj = 0; bj < 2; ++bj) {
;                     f32x4 x0, x1;
;                     if (mode == 2) { const u32x4 w = *(const u32x4*)(xin_b + off + bj * 128);
;                         x0 = (f32x4){bf_lo(w.x), bf_hi(w.x), bf_lo(w.y), bf_hi(w.y)}; x1 = (f32x4){bf_lo(w.z), bf_hi(w.z), bf_lo(w.w), bf_hi(w.w)}; }
;                     else { const float* src = is_ctx ? cin : xin; x0 = *(const f32x4*)(src + off + bj * 128); x1 = *(const f32x4*)(src + off + bj * 128 + 4); }
;                     const f32x4 y0 = x0 + gv[bj][0] * acc[ai][bj][m][0], y1 = x1 + gv[bj][1] * acc[ai][bj][m][1];
;                     if (mode == 1) { u32x4 o; o.x = cvtpk(y0[0], y0[1]); o.y = cvtpk(y0[2], y0[3]); o.z = cvtpk(y1[0], y1[1]); o.w = cvtpk(y1[2], y1[3]); *(u32x4*)(xout_b + off + bj * 128) = o; }
;                     else { float* dst = is_ctx ? cout : xout; *(f32x4*)(dst + off + bj * 128) = y0; *(f32x4*)(dst + off + bj * 128 + 4) = y1; }
;                 }
.Lepi4_l0:
	v_lshlrev_b32_e32 v162, 2, v161
	v_lshlrev_b32_e32 v163, 1, v161
	s_add_u32 s6, s44, 0x0
	s_addc_u32 s7, s45, 0
	global_load_dwordx4 v[172:175], v162, s[6:7]
	global_load_dwordx4 v[176:179], v162, s[6:7] offset:16
	global_load_dwordx4 v[180:183], v162, s[6:7] offset:512
	global_load_dwordx4 v[184:187], v162, s[6:7] offset:528
	s_add_u32 s6, s44, 0x20000
	s_addc_u32 s7, s45, 0
	global_load_dwordx4 v[188:191], v162, s[6:7]
	global_load_dwordx4 v[192:195], v162, s[6:7] offset:16
	global_load_dwordx4 v[196:199], v162, s[6:7] offset:512
	global_load_dwordx4 v[200:203], v162, s[6:7] offset:528
	s_add_u32 s6, s44, 0x40000
	s_addc_u32 s7, s45, 0
	global_load_dwordx4 v[204:207], v162, s[6:7]
	global_load_dwordx4 v[208:211], v162, s[6:7] offset:16
	s_waitcnt vmcnt(8)
	v_pk_fma_f32 v[142:143], v[142:143], v[74:75], v[174:175]
	v_pk_fma_f32 v[140:141], v[140:141], v[72:73], v[172:173]
	v_pk_fma_f32 v[138:139], v[138:139], v[70:71], v[178:179]
	v_pk_fma_f32 v[136:137], v[136:137], v[68:69], v[176:177]
	global_load_dwordx4 v[172:175], v162, s[6:7] offset:512
	global_load_dwordx4 v[176:179], v162, s[6:7] offset:528
	s_add_u32 s8, s54, 0x0
	s_addc_u32 s9, s55, 0
	v_cvt_pk_bf16_f32 v140, v140, v141
	v_cvt_pk_bf16_f32 v141, v142, v143
	v_cvt_pk_bf16_f32 v142, v136, v137
	v_cvt_pk_bf16_f32 v143, v138, v139
	global_store_dwordx4 v163, v[140:143], s[8:9]
	s_waitcnt vmcnt(9)
	v_pk_fma_f32 v[134:135], v[134:135], v[62:63], v[182:183]
	v_pk_fma_f32 v[132:133], v[132:133], v[60:61], v[180:181]
	v_pk_fma_f32 v[130:131], v[130:131], v[58:59], v[186:187]
	v_pk_fma_f32 v[128:129], v[128:129], v[56:57], v[184:185]
	s_add_u32 s6, s44, 0x60000
	s_addc_u32 s7, s45, 0
	global_load_dwordx4 v[180:183], v162, s[6:7]
	global_load_dwordx4 v[184:187], v162, s[6:7] offset:16
	v_cvt_pk_bf16_f32 v132, v132, v133
	v_cvt_pk_bf16_f32 v133, v134, v135
	v_cvt_pk_bf16_f32 v134, v128, v129
	v_cvt_pk_bf16_f32 v135, v130, v131
	global_store_dwordx4 v163, v[132:135], s[8:9] offset:256
	s_waitcnt vmcnt(10)
	v_pk_fma_f32 v[126:127], v[126:127], v[74:75], v[190:191]
	v_pk_fma_f32 v[124:125], v[124:125], v[72:73], v[188:189]
	v_pk_fma_f32 v[122:123], v[122:123], v[70:71], v[194:195]
	v_pk_fma_f32 v[120:121], v[120:121], v[68:69], v[192:193]
	global_load_dwordx4 v[188:191], v162, s[6:7] offset:512
	global_load_dwordx4 v[192:195], v162, s[6:7] offset:528
	s_add_u32 s8, s54, 0x10000
	s_addc_u32 s9, s55, 0
	v_cvt_pk_bf16_f32 v124, v124, v125
	v_cvt_pk_bf16_f32 v125, v126, v127
	v_cvt_pk_bf16_f32 v126, v120, v121
	v_cvt_pk_bf16_f32 v127, v122, v123
	global_store_dwordx4 v163, v[124:127], s[8:9]
	s_waitcnt vmcnt(11)
	v_pk_fma_f32 v[118:119], v[118:119], v[62:63], v[198:199]
	v_pk_fma_f32 v[116:117], v[116:117], v[60:61], v[196:197]
	v_pk_fma_f32 v[114:115], v[114:115], v[58:59], v[202:203]
	v_pk_fma_f32 v[112:113], v[112:113], v[56:57], v[200:201]
	s_add_u32 s6, s44, 0x100000
	s_addc_u32 s7, s45, 0
	global_load_dwordx4 v[196:199], v162, s[6:7]
	global_load_dwordx4 v[200:203], v162, s[6:7] offset:16
	v_cvt_pk_bf16_f32 v116, v116, v117
	v_cvt_pk_bf16_f32 v117, v118, v119
	v_cvt_pk_bf16_f32 v118, v112, v113
	v_cvt_pk_bf16_f32 v119, v114, v115
	global_store_dwordx4 v163, v[116:119], s[8:9] offset:256
	s_waitcnt vmcnt(12)
	v_pk_fma_f32 v[110:111], v[110:111], v[74:75], v[206:207]
	v_pk_fma_f32 v[108:109], v[108:109], v[72:73], v[204:205]
	v_pk_fma_f32 v[106:107], v[106:107], v[70:71], v[210:211]
	v_pk_fma_f32 v[104:105], v[104:105], v[68:69], v[208:209]
	global_load_dwordx4 v[204:207], v162, s[6:7] offset:512
	global_load_dwordx4 v[208:211], v162, s[6:7] offset:528
	s_add_u32 s8, s54, 0x20000
	s_addc_u32 s9, s55, 0
	v_cvt_pk_bf16_f32 v108, v108, v109
	v_cvt_pk_bf16_f32 v109, v110, v111
	v_cvt_pk_bf16_f32 v110, v104, v105
	v_cvt_pk_bf16_f32 v111, v106, v107
	global_store_dwordx4 v163, v[108:111], s[8:9]
	s_waitcnt vmcnt(13)
	v_pk_fma_f32 v[102:103], v[102:103], v[62:63], v[174:175]
	v_pk_fma_f32 v[100:101], v[100:101], v[60:61], v[172:173]
	v_pk_fma_f32 v[98:99], v[98:99], v[58:59], v[178:179]
	v_pk_fma_f32 v[96:97], v[96:97], v[56:57], v[176:177]
	s_add_u32 s6, s44, 0x120000
	s_addc_u32 s7, s45, 0
	global_load_dwordx4 v[172:175], v162, s[6:7]
	global_load_dwordx4 v[176:179], v162, s[6:7] offset:16
	v_cvt_pk_bf16_f32 v100, v100, v101
	v_cvt_pk_bf16_f32 v101, v102, v103
	v_cvt_pk_bf16_f32 v102, v96, v97
	v_cvt_pk_bf16_f32 v103, v98, v99
	global_store_dwordx4 v163, v[100:103], s[8:9] offset:256
	s_waitcnt vmcnt(13)
	v_pk_fma_f32 v[94:95], v[94:95], v[74:75], v[182:183]
	v_pk_fma_f32 v[92:93], v[92:93], v[72:73], v[180:181]
	v_pk_fma_f32 v[90:91], v[90:91], v[70:71], v[186:187]
	v_pk_fma_f32 v[88:89], v[88:89], v[68:69], v[184:185]
	global_load_dwordx4 v[180:183], v162, s[6:7] offset:512
	global_load_dwordx4 v[184:187], v162, s[6:7] offset:528
	s_add_u32 s8, s54, 0x30000
	s_addc_u32 s9, s55, 0
	v_cvt_pk_bf16_f32 v92, v92, v93
	v_cvt_pk_bf16_f32 v93, v94, v95
	v_cvt_pk_bf16_f32 v94, v88, v89
	v_cvt_pk_bf16_f32 v95, v90, v91
	global_store_dwordx4 v163, v[92:95], s[8:9]
	s_waitcnt vmcnt(13)
	v_pk_fma_f32 v[86:87], v[86:87], v[62:63], v[190:191]
	v_pk_fma_f32 v[84:85], v[84:85], v[60:61], v[188:189]
	v_pk_fma_f32 v[82:83], v[82:83], v[58:59], v[194:195]
	v_pk_fma_f32 v[80:81], v[80:81], v[56:57], v[192:193]
	s_add_u32 s6, s44, 0x140000
	s_addc_u32 s7, s45, 0
	global_load_dwordx4 v[188:191], v162, s[6:7]
	global_load_dwordx4 v[192:195], v162, s[6:7] offset:16
	v_cvt_pk_bf16_f32 v84, v84, v85
	v_cvt_pk_bf16_f32 v85, v86, v87
	v_cvt_pk_bf16_f32 v86, v80, v81
	v_cvt_pk_bf16_f32 v87, v82, v83
	global_store_dwordx4 v163, v[84:87], s[8:9] offset:256
	s_waitcnt vmcnt(13)
; DI unsigned cvtpk(float lo, float hi) { f32x2 v = {lo, hi}; bf16x2_t b = __builtin_convertvector(v, bf16x2_t); return __builtin_bit_cast(unsigned, b); }
;     DI void operator()(const f32x4 (&acc)[2][2][4][2], const pg8::Unit& u, int wr, int wc, int fr, int fq) const {
;     ...
;                 for (int bj = 0; bj < 2; ++bj) {
;                     f32x4 x0, x1;
;                     if (mode == 2) { const u32x4 w = *(const u32x4*)(xin_b + off + bj * 128);
;                         x0 = (f32x4){bf_lo(w.x), bf_hi(w.x), bf_lo(w.y), bf_hi(w.y)}; x1 = (f32x4){bf_lo(w.z), bf_hi(w.z), bf_lo(w.w), bf_hi(w.w)}; }
;                     else { const float* src = is_ctx ? cin : xin; x0 = *(const f32x4*)(src + off + bj * 128); x1 = *(const f32x4*)(src + off + bj * 128 + 4); }
;                     const f32x4 y0 = x0 + gv[bj][0] * acc[ai][bj][m][0], y1 = x1 + gv[bj][1] * acc[ai][bj][m][1];
;                     if (mode == 1) { u32x4 o; o.x = cvtpk(y0[0], y0[1]); o.y = cvtpk(y0[2], y0[3]); o.z = cvtpk(y1[0], y1[1]); o.w = cvtpk(y1[2], y1[3]); *(u32x4*)(xout_b + off + bj * 128) = o; }
;                     else { float* dst = is_ctx ? cout : xout; *(f32x4*)(dst + off + bj * 128) = y0; *(f32x4*)(dst + off + bj * 128 + 4) = y1; }
;                 }
	v_pk_fma_f32 v[78:79], v[78:79], v[74:75], v[198:199]
	v_pk_fma_f32 v[76:77], v[76:77], v[72:73], v[196:197]
	v_pk_fma_f32 v[66:67], v[66:67], v[70:71], v[202:203]
	v_pk_fma_f32 v[64:65], v[64:65], v[68:69], v[200:201]
	global_load_dwordx4 v[196:199], v162, s[6:7] offset:512
	global_load_dwordx4 v[200:203], v162, s[6:7] offset:528
	s_add_u32 s8, s54, 0x80000
	s_addc_u32 s9, s55, 0
	v_cvt_pk_bf16_f32 v76, v76, v77
	v_cvt_pk_bf16_f32 v77, v78, v79
	v_cvt_pk_bf16_f32 v78, v64, v65
	v_cvt_pk_bf16_f32 v79, v66, v67
	global_store_dwordx4 v163, v[76:79], s[8:9]
	s_waitcnt vmcnt(13)
	v_pk_fma_f32 v[54:55], v[54:55], v[62:63], v[206:207]
	v_pk_fma_f32 v[52:53], v[52:53], v[60:61], v[204:205]
	v_pk_fma_f32 v[50:51], v[50:51], v[58:59], v[210:211]
	v_pk_fma_f32 v[48:49], v[48:49], v[56:57], v[208:209]
	s_add_u32 s6, s44, 0x160000
	s_addc_u32 s7, s45, 0
	global_load_dwordx4 v[204:207], v162, s[6:7]
	global_load_dwordx4 v[208:211], v162, s[6:7] offset:16
	v_cvt_pk_bf16_f32 v52, v52, v53
	v_cvt_pk_bf16_f32 v53, v54, v55
	v_cvt_pk_bf16_f32 v54, v48, v49
	v_cvt_pk_bf16_f32 v55, v50, v51
	global_store_dwordx4 v163, v[52:55], s[8:9] offset:256
	s_waitcnt vmcnt(13)
	v_pk_fma_f32 v[46:47], v[46:47], v[74:75], v[174:175]
	v_pk_fma_f32 v[44:45], v[44:45], v[72:73], v[172:173]
	v_pk_fma_f32 v[42:43], v[42:43], v[70:71], v[178:179]
	v_pk_fma_f32 v[40:41], v[40:41], v[68:69], v[176:177]
	global_load_dwordx4 v[172:175], v162, s[6:7] offset:512
	global_load_dwordx4 v[176:179], v162, s[6:7] offset:528
	s_add_u32 s8, s54, 0x90000
	s_addc_u32 s9, s55, 0
	v_cvt_pk_bf16_f32 v44, v44, v45
	v_cvt_pk_bf16_f32 v45, v46, v47
	v_cvt_pk_bf16_f32 v46, v40, v41
	v_cvt_pk_bf16_f32 v47, v42, v43
	global_store_dwordx4 v163, v[44:47], s[8:9]
	s_waitcnt vmcnt(13)
	v_pk_fma_f32 v[38:39], v[38:39], v[62:63], v[182:183]
	v_pk_fma_f32 v[36:37], v[36:37], v[60:61], v[180:181]
	v_pk_fma_f32 v[34:35], v[34:35], v[58:59], v[186:187]
	v_pk_fma_f32 v[32:33], v[32:33], v[56:57], v[184:185]
	v_cvt_pk_bf16_f32 v36, v36, v37
	v_cvt_pk_bf16_f32 v37, v38, v39
	v_cvt_pk_bf16_f32 v38, v32, v33
	v_cvt_pk_bf16_f32 v39, v34, v35
	global_store_dwordx4 v163, v[36:39], s[8:9] offset:256
	s_waitcnt vmcnt(11)
	v_pk_fma_f32 v[30:31], v[30:31], v[74:75], v[190:191]
	v_pk_fma_f32 v[28:29], v[28:29], v[72:73], v[188:189]
	v_pk_fma_f32 v[26:27], v[26:27], v[70:71], v[194:195]
	v_pk_fma_f32 v[24:25], v[24:25], v[68:69], v[192:193]
	s_add_u32 s8, s54, 0xa0000
	s_addc_u32 s9, s55, 0
	v_cvt_pk_bf16_f32 v28, v28, v29
	v_cvt_pk_bf16_f32 v29, v30, v31
	v_cvt_pk_bf16_f32 v30, v24, v25
	v_cvt_pk_bf16_f32 v31, v26, v27
	global_store_dwordx4 v163, v[28:31], s[8:9]
	s_waitcnt vmcnt(9)
	v_pk_fma_f32 v[22:23], v[22:23], v[62:63], v[198:199]
	v_pk_fma_f32 v[20:21], v[20:21], v[60:61], v[196:197]
	v_pk_fma_f32 v[18:19], v[18:19], v[58:59], v[202:203]
	v_pk_fma_f32 v[16:17], v[16:17], v[56:57], v[200:201]
	v_cvt_pk_bf16_f32 v20, v20, v21
	v_cvt_pk_bf16_f32 v21, v22, v23
	v_cvt_pk_bf16_f32 v22, v16, v17
	v_cvt_pk_bf16_f32 v23, v18, v19
	global_store_dwordx4 v163, v[20:23], s[8:9] offset:256
	s_waitcnt vmcnt(7)
	v_pk_fma_f32 v[14:15], v[14:15], v[74:75], v[206:207]
	v_pk_fma_f32 v[12:13], v[12:13], v[72:73], v[204:205]
	v_pk_fma_f32 v[10:11], v[10:11], v[70:71], v[210:211]
	v_pk_fma_f32 v[8:9], v[8:9], v[68:69], v[208:209]
	s_add_u32 s8, s54, 0xb0000
	s_addc_u32 s9, s55, 0
	v_cvt_pk_bf16_f32 v12, v12, v13
	v_cvt_pk_bf16_f32 v13, v14, v15
	v_cvt_pk_bf16_f32 v14, v8, v9
	v_cvt_pk_bf16_f32 v15, v10, v11
	global_store_dwordx4 v163, v[12:15], s[8:9]
	s_waitcnt vmcnt(5)
	v_pk_fma_f32 v[6:7], v[6:7], v[62:63], v[174:175]
	v_pk_fma_f32 v[4:5], v[4:5], v[60:61], v[172:173]
	v_pk_fma_f32 v[2:3], v[2:3], v[58:59], v[178:179]
	v_pk_fma_f32 v[0:1], v[0:1], v[56:57], v[176:177]
	v_cvt_pk_bf16_f32 v4, v4, v5
	v_cvt_pk_bf16_f32 v5, v6, v7
	v_cvt_pk_bf16_f32 v6, v0, v1
	v_cvt_pk_bf16_f32 v7, v2, v3
	global_store_dwordx4 v163, v[4:7], s[8:9] offset:256
	s_branch .LBB0_546
.Lepi4_ctx:
	s_mov_b32 s38, s3
	s_mov_b32 s39, s33
	v_lshlrev_b32_e32 v162, 2, v161
	v_lshlrev_b32_e32 v163, 2, v161
	s_add_u32 s6, s40, 0x0
	s_addc_u32 s7, s41, 0
	global_load_dwordx4 v[172:175], v162, s[6:7]
	global_load_dwordx4 v[176:179], v162, s[6:7] offset:16
	global_load_dwordx4 v[180:183], v162, s[6:7] offset:512
	global_load_dwordx4 v[184:187], v162, s[6:7] offset:528
	s_add_u32 s6, s40, 0x20000
	s_addc_u32 s7, s41, 0
	global_load_dwordx4 v[188:191], v162, s[6:7]
	global_load_dwordx4 v[192:195], v162, s[6:7] offset:16
	global_load_dwordx4 v[196:199], v162, s[6:7] offset:512
	global_load_dwordx4 v[200:203], v162, s[6:7] offset:528
	s_add_u32 s6, s40, 0x40000
	s_addc_u32 s7, s41, 0
	global_load_dwordx4 v[204:207], v162, s[6:7]
	global_load_dwordx4 v[208:211], v162, s[6:7] offset:16
	s_waitcnt vmcnt(8)
	v_pk_fma_f32 v[142:143], v[142:143], v[74:75], v[174:175]
	v_pk_fma_f32 v[140:141], v[140:141], v[72:73], v[172:173]
	v_pk_fma_f32 v[138:139], v[138:139], v[70:71], v[178:179]
	v_pk_fma_f32 v[136:137], v[136:137], v[68:69], v[176:177]
	global_load_dwordx4 v[172:175], v162, s[6:7] offset:512
	global_load_dwordx4 v[176:179], v162, s[6:7] offset:528
	s_add_u32 s8, s38, 0x0
	s_addc_u32 s9, s39, 0
	global_store_dwordx4 v163, v[140:143], s[8:9]
	global_store_dwordx4 v163, v[136:139], s[8:9] offset:16
	s_waitcnt vmcnt(10)
	v_pk_fma_f32 v[134:135], v[134:135], v[62:63], v[182:183]
	v_pk_fma_f32 v[132:133], v[132:133], v[60:61], v[180:181]
	v_pk_fma_f32 v[130:131], v[130:131], v[58:59], v[186:187]
	v_pk_fma_f32 v[128:129], v[128:129], v[56:57], v[184:185]
	s_add_u32 s6, s40, 0x60000
	s_addc_u32 s7, s41, 0
	global_load_dwordx4 v[180:183], v162, s[6:7]
	global_load_dwordx4 v[184:187], v162, s[6:7] offset:16
	global_store_dwordx4 v163, v[132:135], s[8:9] offset:512
	global_store_dwordx4 v163, v[128:131], s[8:9] offset:528
	s_waitcnt vmcnt(12)
; DI unsigned cvtpk(float lo, float hi) { f32x2 v = {lo, hi}; bf16x2_t b = __builtin_convertvector(v, bf16x2_t); return __builtin_bit_cast(unsigned, b); }
;     DI void operator()(const f32x4 (&acc)[2][2][4][2], const pg8::Unit& u, int wr, int wc, int fr, int fq) const {
;     ...
;                 for (int bj = 0; bj < 2; ++bj) {
;                     f32x4 x0, x1;
;                     if (mode == 2) { const u32x4 w = *(const u32x4*)(xin_b + off + bj * 128);
;                         x0 = (f32x4){bf_lo(w.x), bf_hi(w.x), bf_lo(w.y), bf_hi(w.y)}; x1 = (f32x4){bf_lo(w.z), bf_hi(w.z), bf_lo(w.w), bf_hi(w.w)}; }
;                     else { const float* src = is_ctx ? cin : xin; x0 = *(const f32x4*)(src + off + bj * 128); x1 = *(const f32x4*)(src + off + bj * 128 + 4); }
;                     const f32x4 y0 = x0 + gv[bj][0] * acc[ai][bj][m][0], y1 = x1 + gv[bj][1] * acc[ai][bj][m][1];
;                     if (mode == 1) { u32x4 o; o.x = cvtpk(y0[0], y0[1]); o.y = cvtpk(y0[2], y0[3]); o.z = cvtpk(y1[0], y1[1]); o.w = cvtpk(y1[2], y1[3]); *(u32x4*)(xout_b + off + bj * 128) = o; }
;                     else { float* dst = is_ctx ? cout : xout; *(f32x4*)(dst + off + bj * 128) = y0; *(f32x4*)(dst + off + bj * 128 + 4) = y1; }
;                 }
	v_pk_fma_f32 v[126:127], v[126:127], v[74:75], v[190:191]
	v_pk_fma_f32 v[124:125], v[124:125], v[72:73], v[188:189]
	v_pk_fma_f32 v[122:123], v[122:123], v[70:71], v[194:195]
	v_pk_fma_f32 v[120:121], v[120:121], v[68:69], v[192:193]
	global_load_dwordx4 v[188:191], v162, s[6:7] offset:512
	global_load_dwordx4 v[192:195], v162, s[6:7] offset:528
	s_add_u32 s8, s38, 0x20000
	s_addc_u32 s9, s39, 0
	global_store_dwordx4 v163, v[124:127], s[8:9]
	global_store_dwordx4 v163, v[120:123], s[8:9] offset:16
	s_waitcnt vmcnt(14)
	v_pk_fma_f32 v[118:119], v[118:119], v[62:63], v[198:199]
	v_pk_fma_f32 v[116:117], v[116:117], v[60:61], v[196:197]
	v_pk_fma_f32 v[114:115], v[114:115], v[58:59], v[202:203]
	v_pk_fma_f32 v[112:113], v[112:113], v[56:57], v[200:201]
	s_add_u32 s6, s40, 0x100000
	s_addc_u32 s7, s41, 0
	global_load_dwordx4 v[196:199], v162, s[6:7]
	global_load_dwordx4 v[200:203], v162, s[6:7] offset:16
	global_store_dwordx4 v163, v[116:119], s[8:9] offset:512
	global_store_dwordx4 v163, v[112:115], s[8:9] offset:528
	s_waitcnt vmcnt(16)
	v_pk_fma_f32 v[110:111], v[110:111], v[74:75], v[206:207]
	v_pk_fma_f32 v[108:109], v[108:109], v[72:73], v[204:205]
	v_pk_fma_f32 v[106:107], v[106:107], v[70:71], v[210:211]
	v_pk_fma_f32 v[104:105], v[104:105], v[68:69], v[208:209]
	global_load_dwordx4 v[204:207], v162, s[6:7] offset:512
	global_load_dwordx4 v[208:211], v162, s[6:7] offset:528
	s_add_u32 s8, s38, 0x40000
	s_addc_u32 s9, s39, 0
	global_store_dwordx4 v163, v[108:111], s[8:9]
	global_store_dwordx4 v163, v[104:107], s[8:9] offset:16
	s_waitcnt vmcnt(18)
	v_pk_fma_f32 v[102:103], v[102:103], v[62:63], v[174:175]
	v_pk_fma_f32 v[100:101], v[100:101], v[60:61], v[172:173]
	v_pk_fma_f32 v[98:99], v[98:99], v[58:59], v[178:179]
	v_pk_fma_f32 v[96:97], v[96:97], v[56:57], v[176:177]
	s_add_u32 s6, s40, 0x120000
	s_addc_u32 s7, s41, 0
	global_load_dwordx4 v[172:175], v162, s[6:7]
	global_load_dwordx4 v[176:179], v162, s[6:7] offset:16
	global_store_dwordx4 v163, v[100:103], s[8:9] offset:512
	global_store_dwordx4 v163, v[96:99], s[8:9] offset:528
	s_waitcnt vmcnt(18)
	v_pk_fma_f32 v[94:95], v[94:95], v[74:75], v[182:183]
	v_pk_fma_f32 v[92:93], v[92:93], v[72:73], v[180:181]
	v_pk_fma_f32 v[90:91], v[90:91], v[70:71], v[186:187]
	v_pk_fma_f32 v[88:89], v[88:89], v[68:69], v[184:185]
	global_load_dwordx4 v[180:183], v162, s[6:7] offset:512
	global_load_dwordx4 v[184:187], v162, s[6:7] offset:528
	s_add_u32 s8, s38, 0x60000
	s_addc_u32 s9, s39, 0
	global_store_dwordx4 v163, v[92:95], s[8:9]
	global_store_dwordx4 v163, v[88:91], s[8:9] offset:16
	s_waitcnt vmcnt(18)
	v_pk_fma_f32 v[86:87], v[86:87], v[62:63], v[190:191]
	v_pk_fma_f32 v[84:85], v[84:85], v[60:61], v[188:189]
	v_pk_fma_f32 v[82:83], v[82:83], v[58:59], v[194:195]
	v_pk_fma_f32 v[80:81], v[80:81], v[56:57], v[192:193]
	s_add_u32 s6, s40, 0x140000
	s_addc_u32 s7, s41, 0
	global_load_dwordx4 v[188:191], v162, s[6:7]
	global_load_dwordx4 v[192:195], v162, s[6:7] offset:16
	global_store_dwordx4 v163, v[84:87], s[8:9] offset:512
	global_store_dwordx4 v163, v[80:83], s[8:9] offset:528
	s_waitcnt vmcnt(18)
	v_pk_fma_f32 v[78:79], v[78:79], v[74:75], v[198:199]
	v_pk_fma_f32 v[76:77], v[76:77], v[72:73], v[196:197]
	v_pk_fma_f32 v[66:67], v[66:67], v[70:71], v[202:203]
	v_pk_fma_f32 v[64:65], v[64:65], v[68:69], v[200:201]
	global_load_dwordx4 v[196:199], v162, s[6:7] offset:512
	global_load_dwordx4 v[200:203], v162, s[6:7] offset:528
	s_add_u32 s8, s38, 0x100000
	s_addc_u32 s9, s39, 0
	global_store_dwordx4 v163, v[76:79], s[8:9]
	global_store_dwordx4 v163, v[64:67], s[8:9] offset:16
	s_waitcnt vmcnt(18)
	v_pk_fma_f32 v[54:55], v[54:55], v[62:63], v[206:207]
	v_pk_fma_f32 v[52:53], v[52:53], v[60:61], v[204:205]
	v_pk_fma_f32 v[50:51], v[50:51], v[58:59], v[210:211]
	v_pk_fma_f32 v[48:49], v[48:49], v[56:57], v[208:209]
	s_add_u32 s6, s40, 0x160000
	s_addc_u32 s7, s41, 0
	global_load_dwordx4 v[204:207], v162, s[6:7]
	global_load_dwordx4 v[208:211], v162, s[6:7] offset:16
	global_store_dwordx4 v163, v[52:55], s[8:9] offset:512
	global_store_dwordx4 v163, v[48:51], s[8:9] offset:528
	s_waitcnt vmcnt(18)
	v_pk_fma_f32 v[46:47], v[46:47], v[74:75], v[174:175]
	v_pk_fma_f32 v[44:45], v[44:45], v[72:73], v[172:173]
	v_pk_fma_f32 v[42:43], v[42:43], v[70:71], v[178:179]
	v_pk_fma_f32 v[40:41], v[40:41], v[68:69], v[176:177]
	global_load_dwordx4 v[172:175], v162, s[6:7] offset:512
	global_load_dwordx4 v[176:179], v162, s[6:7] offset:528
	s_add_u32 s8, s38, 0x120000
	s_addc_u32 s9, s39, 0
	global_store_dwordx4 v163, v[44:47], s[8:9]
	global_store_dwordx4 v163, v[40:43], s[8:9] offset:16
	s_waitcnt vmcnt(18)
	v_pk_fma_f32 v[38:39], v[38:39], v[62:63], v[182:183]
	v_pk_fma_f32 v[36:37], v[36:37], v[60:61], v[180:181]
	v_pk_fma_f32 v[34:35], v[34:35], v[58:59], v[186:187]
	v_pk_fma_f32 v[32:33], v[32:33], v[56:57], v[184:185]
	global_store_dwordx4 v163, v[36:39], s[8:9] offset:512
	global_store_dwordx4 v163, v[32:35], s[8:9] offset:528
	s_waitcnt vmcnt(16)
	v_pk_fma_f32 v[30:31], v[30:31], v[74:75], v[190:191]
	v_pk_fma_f32 v[28:29], v[28:29], v[72:73], v[188:189]
	v_pk_fma_f32 v[26:27], v[26:27], v[70:71], v[194:195]
	v_pk_fma_f32 v[24:25], v[24:25], v[68:69], v[192:193]
	s_add_u32 s8, s38, 0x140000
	s_addc_u32 s9, s39, 0
	global_store_dwordx4 v163, v[28:31], s[8:9]
	global_store_dwordx4 v163, v[24:27], s[8:9] offset:16
	s_waitcnt vmcnt(14)
	v_pk_fma_f32 v[22:23], v[22:23], v[62:63], v[198:199]
	v_pk_fma_f32 v[20:21], v[20:21], v[60:61], v[196:197]
	v_pk_fma_f32 v[18:19], v[18:19], v[58:59], v[202:203]
	v_pk_fma_f32 v[16:17], v[16:17], v[56:57], v[200:201]
	global_store_dwordx4 v163, v[20:23], s[8:9] offset:512
	global_store_dwordx4 v163, v[16:19], s[8:9] offset:528
	s_waitcnt vmcnt(12)
	v_pk_fma_f32 v[14:15], v[14:15], v[74:75], v[206:207]
	v_pk_fma_f32 v[12:13], v[12:13], v[72:73], v[204:205]
	v_pk_fma_f32 v[10:11], v[10:11], v[70:71], v[210:211]
	v_pk_fma_f32 v[8:9], v[8:9], v[68:69], v[208:209]
	s_add_u32 s8, s38, 0x160000
	s_addc_u32 s9, s39, 0
	global_store_dwordx4 v163, v[12:15], s[8:9]
	global_store_dwordx4 v163, v[8:11], s[8:9] offset:16
	s_waitcnt vmcnt(10)
	v_pk_fma_f32 v[6:7], v[6:7], v[62:63], v[174:175]
	v_pk_fma_f32 v[4:5], v[4:5], v[60:61], v[172:173]
	v_pk_fma_f32 v[2:3], v[2:3], v[58:59], v[178:179]
	v_pk_fma_f32 v[0:1], v[0:1], v[56:57], v[176:177]
	global_store_dwordx4 v163, v[4:7], s[8:9] offset:512
	global_store_dwordx4 v163, v[0:3], s[8:9] offset:528
	s_branch .LBB0_546
.LBB0_546:
	s_andn2_b64 vcc, exec, s[60:61]
	s_mov_b64 s[36:37], -1
	s_cbranch_vccnz .LBB0_411
	s_branch .LBB0_549
.LBB0_549:
	s_andn2_b64 vcc, exec, s[16:17]
	s_cbranch_vccnz .LBB0_410
	s_barrier
	s_branch .LBB0_410
